# c11: adds a fast flush path for non-permuted in-proj destinations
# speedup vs baseline: 1.0445x; 1.0022x over previous
; __device__ void gemm1_phase(const Params& p, int l, int hb, unsigned char* smem) {
;     ...
;         if (dbase) {
;             const int ch = lane & 7;
; #pragma unroll
;             for (int j = 0; j < 16; ++j) {
;                 const int rl = 8 * j + (lane >> 3), row = m0 + wm * 128 + rl;
;                 const u32x4 v = *(const u32x4*)(wl + rl * 128 + ((ch ^ (rl & 7)) * 16));
;                 size_t drow = (size_t)row;
;                 if (dsh >= 0) { const int bl = row >> 13, tt = row & (SEQ - 1); drow = (size_t)(bl * 3 + dg) * SEQ + (size_t)((tt & ((1 << dsh) - 1)) * (SEQ >> dsh) + (tt >> dsh)); }
;                 *(u32x4*)(dbase + drow * dpitch + dc0 + ch * 8) = v;
;             }
;         }
.LBB0_522:
	s_cmp_gt_i32 s50, -1
	s_cbranch_scc1 .Lg1_flush_perm
	v_lshrrev_b32_e32 v40, 3, v230
	v_and_b32_e32 v41, 7, v181
	v_xor_b32_e32 v42, v41, v40
	v_lshl_add_u32 v42, v42, 4, s61
	v_lshl_add_u32 v42, v40, 7, v42
	s_lshl_b32 s12, s57, 7
	s_add_i32 s12, s12, s56
	v_add_u32_e32 v40, s12, v40
	v_mul_lo_u32 v40, v40, s88
	v_add_u32_e32 v40, s58, v40
	v_lshlrev_b32_e32 v40, 1, v40
	v_lshl_add_u32 v40, v41, 4, v40
	s_lshl_b32 s99, s88, 4
	ds_read_b128 v[0:3], v42
	ds_read_b128 v[4:7], v42 offset:1024
	ds_read_b128 v[8:11], v42 offset:2048
	ds_read_b128 v[12:15], v42 offset:3072
	ds_read_b128 v[16:19], v42 offset:4096
	ds_read_b128 v[20:23], v42 offset:5120
	ds_read_b128 v[24:27], v42 offset:6144
	ds_read_b128 v[28:31], v42 offset:7168
	s_waitcnt lgkmcnt(7)
	global_store_dwordx4 v40, v[0:3], s[90:91]
	v_add_u32_e32 v40, s99, v40
	s_waitcnt lgkmcnt(6)
	global_store_dwordx4 v40, v[4:7], s[90:91]
	v_add_u32_e32 v40, s99, v40
	s_waitcnt lgkmcnt(5)
	global_store_dwordx4 v40, v[8:11], s[90:91]
	v_add_u32_e32 v40, s99, v40
	s_waitcnt lgkmcnt(4)
	global_store_dwordx4 v40, v[12:15], s[90:91]
	v_add_u32_e32 v40, s99, v40
	s_waitcnt lgkmcnt(3)
	global_store_dwordx4 v40, v[16:19], s[90:91]
	v_add_u32_e32 v40, s99, v40
	s_waitcnt lgkmcnt(2)
	global_store_dwordx4 v40, v[20:23], s[90:91]
	v_add_u32_e32 v40, s99, v40
	s_waitcnt lgkmcnt(1)
	global_store_dwordx4 v40, v[24:27], s[90:91]
	v_add_u32_e32 v40, s99, v40
	s_waitcnt lgkmcnt(0)
	global_store_dwordx4 v40, v[28:31], s[90:91]
	v_add_u32_e32 v40, s99, v40
	ds_read_b128 v[0:3], v42 offset:8192
	ds_read_b128 v[4:7], v42 offset:9216
	ds_read_b128 v[8:11], v42 offset:10240
	ds_read_b128 v[12:15], v42 offset:11264
	ds_read_b128 v[16:19], v42 offset:12288
	ds_read_b128 v[20:23], v42 offset:13312
	ds_read_b128 v[24:27], v42 offset:14336
	ds_read_b128 v[28:31], v42 offset:15360
	s_waitcnt lgkmcnt(7)
	global_store_dwordx4 v40, v[0:3], s[90:91]
	v_add_u32_e32 v40, s99, v40
	s_waitcnt lgkmcnt(6)
	global_store_dwordx4 v40, v[4:7], s[90:91]
	v_add_u32_e32 v40, s99, v40
	s_waitcnt lgkmcnt(5)
	global_store_dwordx4 v40, v[8:11], s[90:91]
	v_add_u32_e32 v40, s99, v40
	s_waitcnt lgkmcnt(4)
	global_store_dwordx4 v40, v[12:15], s[90:91]
	v_add_u32_e32 v40, s99, v40
	s_waitcnt lgkmcnt(3)
	global_store_dwordx4 v40, v[16:19], s[90:91]
	v_add_u32_e32 v40, s99, v40
	s_waitcnt lgkmcnt(2)
	global_store_dwordx4 v40, v[20:23], s[90:91]
	v_add_u32_e32 v40, s99, v40
	s_waitcnt lgkmcnt(1)
	global_store_dwordx4 v40, v[24:27], s[90:91]
	v_add_u32_e32 v40, s99, v40
	s_waitcnt lgkmcnt(0)
	global_store_dwordx4 v40, v[28:31], s[90:91]
	v_add_u32_e32 v40, s99, v40
	s_branch .LBB0_253
